# 5b2: expert-id row load hoisted next to the other loads of the item (one memory round trip per item less)
# speedup vs baseline: 1.0056x; 1.0056x over previous
; DI void phase5b2(const Params& p) {
;     ...
;   for (size_t i = (size_t)blockIdx.x * 256 + threadIdx.x; i < n4; i += (size_t)gridDim.x * 256) {
;     float4 a = make_float4(0.f, 0.f, 0.f, 0.f);
; #pragma unroll
;     for (int j = 0; j < 8; ++j) {
;       const uint2 v = ((const uint2*)part_ptr(ws, j))[i];
;       a.x += __uint_as_float(v.x << 16); a.y += __uint_as_float(v.x & 0xffff0000u);
;       a.z += __uint_as_float(v.y << 16); a.w += __uint_as_float(v.y & 0xffff0000u);
;     }
;     const float4 g = selg[i];
;     float av[4] = {a.x, a.y, a.z, a.w}, gv[4] = {g.x, g.y, g.z, g.w}, o[4];
; #pragma unroll
;     for (int j = 0; j < 4; ++j) {
;       const float x = av[j] * (1.0f / 32.0f);
;       o[j] = gv[j] * 0.5f * x * (1.0f + erff(x * 0.7071067811865476f)) * 0.125f;
;     }
;     const uint2 ee = sele4[i];
;     pw[i] = make_uint4(((ee.x & 0xffffu) << 16) | f2bf(o[0]), (ee.x & 0xffff0000u) | f2bf(o[1]),
;                        ((ee.y & 0xffffu) << 16) | f2bf(o[2]), (ee.y & 0xffff0000u) | f2bf(o[3]));
.LBB0_397:
	s_or_b64 exec, exec, s[26:27]
	v_add_co_u32_e32 v10, vcc, s38, v10
	s_waitcnt vmcnt(0)
	v_mul_f32_e32 v2, 0.5, v2
	v_addc_co_u32_e32 v11, vcc, 0, v11, vcc
	v_mov_b32_e32 v10, v42
	v_mov_b32_e32 v11, v43
	v_bfi_b32 v21, s37, v24, v22
	v_mul_f32_e32 v3, 0.5, v3
	v_mul_f32_e32 v1, 0.5, v1
	v_bfi_b32 v16, s37, v18, v16
	v_mul_f32_e32 v0, 0.5, v0
	v_bfi_b32 v18, s37, v35, v34
	v_bfi_b32 v17, s37, v19, v17
	v_mul_f32_e32 v2, v2, v20
	v_add_f32_e32 v19, 1.0, v21
	v_mul_f32_e32 v3, v15, v3
	v_mul_f32_e32 v1, v1, v14
	v_add_f32_e32 v14, 1.0, v16
	v_mul_f32_e32 v0, v0, v33
	v_add_f32_e32 v15, 1.0, v18
	v_add_f32_e32 v16, 1.0, v17
	v_add_co_u32_e32 v12, vcc, 0x9188000, v12
	v_mul_f32_e32 v2, v2, v19
	v_mul_f32_e32 v1, v1, v14
	v_mul_f32_e32 v0, v0, v15
	v_mul_f32_e32 v3, v3, v16
	v_lshl_add_u64 v[4:5], v[4:5], 0, s[10:11]
	v_addc_co_u32_e32 v13, vcc, 0, v13, vcc
	v_mul_f32_e32 v2, 0x3e000000, v2
	v_mul_f32_e32 v1, 0x3e000000, v1
	v_mul_f32_e32 v0, 0x3e000000, v0
	v_mul_f32_e32 v3, 0x3e000000, v3
	v_cmp_lt_u64_e32 vcc, s[24:25], v[4:5]
	v_cvt_pk_bf16_f32 v0, v0, v1
	v_cvt_pk_bf16_f32 v2, v2, v3
	v_lshl_add_u64 v[6:7], v[6:7], 0, s[16:17]
	s_or_b64 s[22:23], vcc, s[22:23]
	v_lshl_add_u64 v[8:9], v[8:9], 0, s[20:21]
	s_waitcnt vmcnt(0)
	v_lshlrev_b32_e32 v3, 16, v10
	v_and_b32_e32 v1, 0xffff0000, v10
	v_lshlrev_b32_e32 v10, 16, v11
	v_and_b32_e32 v11, 0xffff0000, v11
	v_or_b32_sdwa v1, v1, v0 dst_sel:DWORD dst_unused:UNUSED_PAD src0_sel:DWORD src1_sel:WORD_1
	v_or_b32_sdwa v0, v3, v0 dst_sel:DWORD dst_unused:UNUSED_PAD src0_sel:DWORD src1_sel:WORD_0
	v_or_b32_sdwa v3, v11, v2 dst_sel:DWORD dst_unused:UNUSED_PAD src0_sel:DWORD src1_sel:WORD_1
	v_or_b32_sdwa v2, v10, v2 dst_sel:DWORD dst_unused:UNUSED_PAD src0_sel:DWORD src1_sel:WORD_0
	global_store_dwordx4 v[12:13], v[0:3], off
	s_andn2_b64 exec, exec, s[22:23]
	s_cbranch_execz .LBB0_414
.LBB0_398:
	v_lshl_add_u64 v[10:11], s[14:15], 0, v[6:7]
	v_add_co_u32_e32 v40, vcc, s38, v10
	s_nop 1
	v_addc_co_u32_e32 v41, vcc, 0, v11, vcc
	global_load_dwordx2 v[42:43], v[40:41], off
	v_add_co_u32_e32 v0, vcc, 0x15188000, v10
	s_nop 1
	v_addc_co_u32_e32 v1, vcc, 0, v11, vcc
	v_add_co_u32_e32 v2, vcc, 0x16988000, v10
	s_nop 1
	v_addc_co_u32_e32 v3, vcc, 0, v11, vcc
	v_add_co_u32_e32 v12, vcc, 0x18188000, v10
	s_nop 1
	v_addc_co_u32_e32 v13, vcc, 0, v11, vcc
	v_add_co_u32_e32 v22, vcc, 0x19988000, v10
	s_nop 1
	v_addc_co_u32_e32 v23, vcc, 0, v11, vcc
	global_load_dwordx2 v[20:21], v[0:1], off
	global_load_dwordx2 v[16:17], v[2:3], off
	global_load_dwordx2 v[14:15], v[12:13], off
	global_load_dwordx2 v[18:19], v[22:23], off
	v_add_co_u32_e32 v0, vcc, 0x1b188000, v10
	s_waitcnt vmcnt(3)
	v_lshlrev_b32_e32 v33, 16, v20
	v_addc_co_u32_e32 v1, vcc, 0, v11, vcc
	global_load_dwordx2 v[22:23], v[0:1], off
	v_add_co_u32_e32 v0, vcc, 0x1c988000, v10
	v_add_f32_e32 v33, 0, v33
	s_nop 0
	v_addc_co_u32_e32 v1, vcc, 0, v11, vcc
	v_add_co_u32_e32 v2, vcc, 0x1e188000, v10
	s_waitcnt vmcnt(3)
	v_lshlrev_b32_e32 v34, 16, v16
	v_addc_co_u32_e32 v3, vcc, 0, v11, vcc
	v_add_co_u32_e32 v12, vcc, 0x1f988000, v10
	v_add_f32_e32 v33, v33, v34
	s_nop 0
	v_addc_co_u32_e32 v13, vcc, 0, v11, vcc
	global_load_dwordx2 v[26:27], v[0:1], off
	global_load_dwordx2 v[24:25], v[2:3], off
	global_load_dwordx2 v[28:29], v[12:13], off
	v_lshl_add_u64 v[12:13], s[14:15], 0, v[8:9]
	v_add_co_u32_e32 v0, vcc, 0xd988000, v12
	s_waitcnt vmcnt(5)
	v_lshlrev_b32_e32 v34, 16, v14
	v_addc_co_u32_e32 v1, vcc, 0, v13, vcc
	global_load_dwordx4 v[0:3], v[0:1], off
	v_add_f32_e32 v33, v33, v34
	s_waitcnt vmcnt(5)
	v_lshlrev_b32_e32 v34, 16, v18
	v_add_f32_e32 v33, v33, v34
	s_waitcnt vmcnt(4)
	v_lshlrev_b32_e32 v34, 16, v22
	v_add_f32_e32 v33, v33, v34
	s_waitcnt vmcnt(3)
	v_lshlrev_b32_e32 v34, 16, v26
	v_add_f32_e32 v33, v33, v34
	s_waitcnt vmcnt(2)
	v_lshlrev_b32_e32 v34, 16, v24
	v_add_f32_e32 v33, v33, v34
	s_waitcnt vmcnt(1)
	v_lshlrev_b32_e32 v34, 16, v28
	v_add_f32_e32 v33, v33, v34
	v_mul_f32_e32 v33, 0x3d000000, v33
	v_mul_f32_e32 v34, 0x3f3504f3, v33
	v_cmp_nlt_f32_e64 s[26:27], |v34|, 1.0
	s_and_saveexec_b64 s[40:41], s[26:27]
	s_xor_b64 s[26:27], exec, s[40:41]
	s_cbranch_execz .LBB0_400
	v_fma_f32 v35, |v34|, s3, v31
	v_fma_f32 v35, |v34|, v35, s13
	v_fma_f32 v35, |v34|, v35, s28
	v_fma_f32 v35, |v34|, v35, s29
	v_fma_f32 v35, |v34|, v35, s30
	v_fma_f32 v35, |v34|, v35, s31
	v_fma_f32 v35, |v34|, v35, |v34|
	v_mul_f32_e32 v36, 0xbfb8aa3b, v35
	v_fma_f32 v37, v35, s34, -v36
	v_rndne_f32_e32 v38, v36
	v_fmac_f32_e32 v37, 0xb2a5705f, v35
	v_sub_f32_e32 v36, v36, v38
	v_add_f32_e32 v36, v36, v37
	v_cvt_i32_f32_e32 v37, v38
	v_exp_f32_e32 v36, v36
	v_cmp_nlt_f32_e32 vcc, s35, v35
	v_ldexp_f32 v36, v36, v37
	s_nop 0
	v_cndmask_b32_e32 v36, 0, v36, vcc
	v_cmp_ngt_f32_e32 vcc, s36, v35
	s_nop 1
	v_cndmask_b32_e32 v35, v32, v36, vcc
	v_sub_f32_e32 v35, 1.0, v35
